# RWKV scan wave instruction stream slimmed: chained dot products (no packed adds), A/B row chains interleaved with extra temp (nops gone), dpp mov+add merged, ds_write addresses hoisted into dpp gaps,
# speedup vs baseline: 1.0211x; 1.0106x over previous
; __device__ __forceinline__ void phase_rwkv(KP P, int l_, unsigned char* shm) {
;     ...
;                 const float* cf = sCoef + (c & 1) * CS; const float* vb = sV + (c % 3) * T * 64; float* ob = sO + (c & 1) * T * 64;
;     ...
;                 f32x4 Aw0, Aw1, Akk0, Akk1, Ab0, Ab1, Ak0, Ak1, Ar0, Ar1; float Ava, Avb;
;                 f32x4 Bw0, Bw1, Bkk0, Bkk1, Bb0, Bb1, Bk0, Bk1, Br0, Br1; float Bva, Bvb;
;                 RW_LD(A, 0);
.LBB0_2515:
	s_and_b32 s1, s42, 1
	s_waitcnt vmcnt(26)
	v_cndmask_b32_e64 v0, 0, 1, s[78:79]
	s_mov_b32 s0, 0xa000
	s_mul_i32 s1, s1, 0xa000
	s_mul_i32 s43, s42, 0xab
	v_lshl_or_b32 v253, v0, 13, v173
	v_mul_lo_u32 v0, v0, s0
	s_bfe_u32 s43, s43, 0x70009
	s_waitcnt vmcnt(17)
	v_add_u32_e32 v14, s1, v156
	v_or_b32_e32 v235, v174, v0
	s_mul_i32 s43, s43, 3
	s_waitcnt vmcnt(12)
	ds_read_b128 v[10:13], v14
	ds_read_b128 v[0:3], v14 offset:16
	s_waitcnt vmcnt(0)
	ds_read_b128 v[38:41], v14 offset:8192
	ds_read_b128 v[34:37], v14 offset:8208
	ds_read_b128 v[26:29], v14 offset:16384
	ds_read_b128 v[6:9], v14 offset:16400
	ds_read_b128 v[30:33], v14 offset:24576
	ds_read_b128 v[22:25], v14 offset:24592
	s_sub_i32 s43, s42, s43
	s_and_b32 s43, s43, 0xff
	s_lshl_b32 s43, s43, 13
	s_add_i32 s43, s43, 0
	v_lshl_add_u32 v4, v123, 2, s43
	v_add_u32_e32 v4, 0x14000, v4
	s_mul_hi_u32 s0, s42, 0xaaaaaaab
	ds_read2_b32 v[106:107], v4 offset1:32
	ds_read_b128 v[18:21], v14 offset:32768
	ds_read_b128 v[14:17], v14 offset:32784
	s_lshr_b32 s0, s0, 1
	s_mulk_i32 s0, 0xa000
	s_add_i32 s43, s0, 0
	s_mov_b32 s52, -2
	v_mov_b32_e32 v252, v175
	s_waitcnt lgkmcnt(2)
	s_branch .LBB0_2517

; __device__ __forceinline__ void phase_rwkv(KP P, int l_, unsigned char* shm) {
;     ...
;                 f32x4 Aw0, Aw1, Akk0, Akk1, Ab0, Ab1, Ak0, Ak1, Ar0, Ar1; float Ava, Avb;
;                 f32x4 Bw0, Bw1, Bkk0, Bkk1, Bb0, Bb1, Bk0, Bk1, Br0, Br1; float Bva, Bvb;
;                 RW_LD(A, 0);
; #pragma unroll 2
;                 for (int tl = 0; tl < T; tl += 2) {
;                     RW_LD(B, tl + 1);
;                     RW_STEP(A, tl);
;                     RW_LD(A, tl + 2);
;                     RW_STEP(B, tl + 1);
;                 }
.LBB0_2517:
	v_pk_mul_f32 v[110:111], v[40:41], v[92:93]
	v_pk_mul_f32 v[40:41], v[40:41], v[100:101]
	v_pk_fma_f32 v[110:111], v[38:39], v[90:91], v[110:111]
	v_pk_fma_f32 v[38:39], v[38:39], v[98:99], v[40:41]
	v_pk_fma_f32 v[40:41], v[36:37], v[96:97], v[110:111]
	v_pk_fma_f32 v[36:37], v[36:37], v[104:105], v[38:39]
	v_pk_fma_f32 v[40:41], v[34:35], v[94:95], v[40:41]
	v_pk_fma_f32 v[34:35], v[34:35], v[102:103], v[36:37]
	v_add_f32_e32 v36, v40, v41
	v_add_f32_e32 v34, v34, v35
	ds_read_b128 v[62:65], v235
	v_add_f32_dpp v35, v36, v36 quad_perm:[1,0,3,2] row_mask:0xf bank_mask:0xf bound_ctrl:1
	v_add_f32_dpp v34, v34, v34 quad_perm:[1,0,3,2] row_mask:0xf bank_mask:0xf bound_ctrl:1
	ds_read_b128 v[50:53], v235 offset:16
	ds_read_b128 v[78:81], v235 offset:8192
	ds_read_b128 v[74:77], v235 offset:8208
	ds_read_b128 v[66:69], v235 offset:16384
	ds_read_b128 v[54:57], v235 offset:16400
	ds_read_b128 v[70:73], v235 offset:24576
	ds_read_b128 v[58:61], v235 offset:24592
	ds_read_b128 v[46:49], v235 offset:32768
	ds_read_b128 v[42:45], v235 offset:32784
	v_add_f32_dpp v35, v35, v35 quad_perm:[2,3,0,1] row_mask:0xf bank_mask:0xf bound_ctrl:1
	v_add_f32_dpp v36, v34, v34 quad_perm:[2,3,0,1] row_mask:0xf bank_mask:0xf bound_ctrl:1
	v_add_u32_e32 v186, s43, v252
	v_add_f32_dpp v34, v35, v35 row_half_mirror row_mask:0xf bank_mask:0xf bound_ctrl:1
	v_add_f32_dpp v36, v36, v36 row_half_mirror row_mask:0xf bank_mask:0xf bound_ctrl:1
	v_pk_mul_f32 v[38:39], v[26:27], v[34:35] op_sel_hi:[1,0] neg_lo:[0,1] neg_hi:[0,1]
	v_pk_mul_f32 v[26:27], v[26:27], v[36:37] op_sel_hi:[1,0] neg_lo:[0,1] neg_hi:[0,1]
	v_pk_fma_f32 v[38:39], v[10:11], v[90:91], v[38:39]
	v_pk_fma_f32 v[10:11], v[10:11], v[98:99], v[26:27]
	s_waitcnt lgkmcnt(13)
	v_pk_fma_f32 v[110:111], v[30:31], v[106:107], v[38:39] op_sel_hi:[1,0,1]
	v_pk_fma_f32 v[98:99], v[30:31], v[106:107], v[10:11] op_sel:[0,1,0]
	v_pk_mul_f32 v[10:11], v[28:29], v[34:35] op_sel_hi:[1,0] neg_lo:[0,1] neg_hi:[0,1]
	v_pk_mul_f32 v[170:171], v[28:29], v[36:37] op_sel_hi:[1,0] neg_lo:[0,1] neg_hi:[0,1]
	ds_read2_b32 v[108:109], v186 offset1:32
	v_pk_fma_f32 v[10:11], v[12:13], v[92:93], v[10:11]
	v_pk_fma_f32 v[170:171], v[12:13], v[100:101], v[170:171]
	v_pk_fma_f32 v[92:93], v[32:33], v[106:107], v[10:11] op_sel_hi:[1,0,1]
	v_pk_fma_f32 v[100:101], v[32:33], v[106:107], v[170:171] op_sel:[0,1,0]
	v_pk_mul_f32 v[10:11], v[6:7], v[34:35] op_sel_hi:[1,0] neg_lo:[0,1] neg_hi:[0,1]
	v_pk_mul_f32 v[6:7], v[6:7], v[36:37] op_sel_hi:[1,0] neg_lo:[0,1] neg_hi:[0,1]
	v_pk_fma_f32 v[10:11], v[0:1], v[94:95], v[10:11]
	v_pk_fma_f32 v[0:1], v[0:1], v[102:103], v[6:7]
	s_waitcnt lgkmcnt(13)
	v_pk_fma_f32 v[94:95], v[22:23], v[106:107], v[10:11] op_sel_hi:[1,0,1]
	v_pk_fma_f32 v[102:103], v[22:23], v[106:107], v[0:1] op_sel:[0,1,0]
	v_pk_mul_f32 v[0:1], v[8:9], v[34:35] op_sel_hi:[1,0] neg_lo:[0,1] neg_hi:[0,1]
	v_pk_mul_f32 v[170:171], v[8:9], v[36:37] op_sel_hi:[1,0] neg_lo:[0,1] neg_hi:[0,1]
	v_pk_fma_f32 v[0:1], v[2:3], v[96:97], v[0:1]
	v_pk_fma_f32 v[170:171], v[2:3], v[104:105], v[170:171]
	v_pk_fma_f32 v[96:97], v[24:25], v[106:107], v[0:1] op_sel_hi:[1,0,1]
	v_pk_fma_f32 v[104:105], v[24:25], v[106:107], v[170:171] op_sel:[0,1,0]
	s_waitcnt lgkmcnt(11)
	v_pk_mul_f32 v[2:3], v[20:21], v[100:101]
	v_pk_mul_f32 v[0:1], v[20:21], v[92:93]
	v_pk_fma_f32 v[2:3], v[18:19], v[98:99], v[2:3]
	v_pk_fma_f32 v[0:1], v[18:19], v[110:111], v[0:1]
	v_pk_fma_f32 v[8:9], v[16:17], v[104:105], v[2:3]
	v_pk_fma_f32 v[6:7], v[16:17], v[96:97], v[0:1]
	v_pk_fma_f32 v[8:9], v[14:15], v[102:103], v[8:9]
	v_pk_fma_f32 v[6:7], v[14:15], v[94:95], v[6:7]
	v_add_f32_e32 v1, v8, v9
	v_add_f32_e32 v0, v6, v7
	v_add_u32_e32 v168, 0x1e000, v253
	v_add_f32_dpp v1, v1, v1 quad_perm:[1,0,3,2] row_mask:0xf bank_mask:0xf bound_ctrl:1
	v_add_f32_dpp v0, v0, v0 quad_perm:[1,0,3,2] row_mask:0xf bank_mask:0xf bound_ctrl:1
	v_add_u32_e32 v169, 0x1e080, v253
	v_add_f32_dpp v1, v1, v1 quad_perm:[2,3,0,1] row_mask:0xf bank_mask:0xf bound_ctrl:1
	v_add_f32_dpp v0, v0, v0 quad_perm:[2,3,0,1] row_mask:0xf bank_mask:0xf bound_ctrl:1
	s_nop 0
	v_add_f32_dpp v1, v1, v1 row_half_mirror row_mask:0xf bank_mask:0xf bound_ctrl:1
	v_add_f32_dpp v0, v0, v0 row_half_mirror row_mask:0xf bank_mask:0xf bound_ctrl:1
	s_and_saveexec_b64 s[72:73], s[6:7]
	ds_write_b32 v168, v0
	ds_write_b32 v169, v1
; __device__ __forceinline__ void phase_rwkv(KP P, int l_, unsigned char* shm) {
;     ...
;                 f32x4 Aw0, Aw1, Akk0, Akk1, Ab0, Ab1, Ak0, Ak1, Ar0, Ar1; float Ava, Avb;
;                 f32x4 Bw0, Bw1, Bkk0, Bkk1, Bb0, Bb1, Bk0, Bk1, Br0, Br1; float Bva, Bvb;
;                 RW_LD(A, 0);
; #pragma unroll 2
;                 for (int tl = 0; tl < T; tl += 2) {
;                     RW_LD(B, tl + 1);
;                     RW_STEP(A, tl);
;                     RW_LD(A, tl + 2);
;                     RW_STEP(B, tl + 1);
;                 }
.LBB0_2519:
	s_or_b64 exec, exec, s[72:73]
	s_waitcnt lgkmcnt(8)
	v_pk_mul_f32 v[106:107], v[80:81], v[92:93]
	v_pk_mul_f32 v[80:81], v[80:81], v[100:101]
	v_pk_fma_f32 v[106:107], v[78:79], v[110:111], v[106:107]
	v_pk_fma_f32 v[78:79], v[78:79], v[98:99], v[80:81]
	s_waitcnt lgkmcnt(7)
	v_pk_fma_f32 v[80:81], v[76:77], v[96:97], v[106:107]
	v_pk_fma_f32 v[76:77], v[76:77], v[104:105], v[78:79]
	v_pk_fma_f32 v[80:81], v[74:75], v[94:95], v[80:81]
	v_pk_fma_f32 v[74:75], v[74:75], v[102:103], v[76:77]
	v_add_f32_e32 v4, v80, v81
	v_add_f32_e32 v74, v74, v75
	s_waitcnt lgkmcnt(0)
	v_add_f32_dpp v4, v4, v4 quad_perm:[1,0,3,2] row_mask:0xf bank_mask:0xf bound_ctrl:1
	v_add_f32_dpp v74, v74, v74 quad_perm:[1,0,3,2] row_mask:0xf bank_mask:0xf bound_ctrl:1
	ds_read_b128 v[22:25], v235 offset:256
	ds_read_b128 v[10:13], v235 offset:272
	ds_read_b128 v[38:41], v235 offset:8448
	ds_read_b128 v[34:37], v235 offset:8464
	ds_read_b128 v[26:29], v235 offset:16640
	ds_read_b128 v[14:17], v235 offset:16656
	ds_read_b128 v[30:33], v235 offset:24832
	ds_read_b128 v[18:21], v235 offset:24848
	ds_read_b128 v[6:9], v235 offset:33024
	ds_read_b128 v[0:3], v235 offset:33040
	ds_read2_b32 v[90:91], v186 offset0:64 offset1:96
	v_add_f32_dpp v4, v4, v4 quad_perm:[2,3,0,1] row_mask:0xf bank_mask:0xf bound_ctrl:1
	v_add_f32_dpp v74, v74, v74 quad_perm:[2,3,0,1] row_mask:0xf bank_mask:0xf bound_ctrl:1
	s_nop 0
	v_add_f32_dpp v4, v4, v4 row_half_mirror row_mask:0xf bank_mask:0xf bound_ctrl:1
	v_add_f32_dpp v74, v74, v74 row_half_mirror row_mask:0xf bank_mask:0xf bound_ctrl:1
	v_pk_mul_f32 v[78:79], v[66:67], v[4:5] op_sel_hi:[1,0] neg_lo:[0,1] neg_hi:[0,1]
	v_pk_mul_f32 v[66:67], v[66:67], v[74:75] op_sel_hi:[1,0] neg_lo:[0,1] neg_hi:[0,1]
	v_pk_fma_f32 v[78:79], v[62:63], v[110:111], v[78:79]
	v_pk_fma_f32 v[62:63], v[62:63], v[98:99], v[66:67]
	v_pk_fma_f32 v[106:107], v[70:71], v[108:109], v[78:79] op_sel_hi:[1,0,1]
	v_pk_fma_f32 v[98:99], v[70:71], v[108:109], v[62:63] op_sel:[0,1,0]
	v_pk_mul_f32 v[62:63], v[68:69], v[4:5] op_sel_hi:[1,0] neg_lo:[0,1] neg_hi:[0,1]
	v_pk_mul_f32 v[170:171], v[68:69], v[74:75] op_sel_hi:[1,0] neg_lo:[0,1] neg_hi:[0,1]
	v_pk_fma_f32 v[62:63], v[64:65], v[92:93], v[62:63]
	v_pk_fma_f32 v[170:171], v[64:65], v[100:101], v[170:171]
	v_pk_fma_f32 v[110:111], v[72:73], v[108:109], v[62:63] op_sel_hi:[1,0,1]
	v_pk_fma_f32 v[112:113], v[72:73], v[108:109], v[170:171] op_sel:[0,1,0]
	v_pk_mul_f32 v[62:63], v[54:55], v[4:5] op_sel_hi:[1,0] neg_lo:[0,1] neg_hi:[0,1]
	v_pk_mul_f32 v[54:55], v[54:55], v[74:75] op_sel_hi:[1,0] neg_lo:[0,1] neg_hi:[0,1]
	v_pk_fma_f32 v[62:63], v[50:51], v[94:95], v[62:63]
	v_pk_fma_f32 v[50:51], v[50:51], v[102:103], v[54:55]
	v_pk_fma_f32 v[114:115], v[58:59], v[108:109], v[62:63] op_sel_hi:[1,0,1]
	v_pk_fma_f32 v[116:117], v[58:59], v[108:109], v[50:51] op_sel:[0,1,0]
	v_pk_mul_f32 v[50:51], v[56:57], v[4:5] op_sel_hi:[1,0] neg_lo:[0,1] neg_hi:[0,1]
	v_pk_mul_f32 v[170:171], v[56:57], v[74:75] op_sel_hi:[1,0] neg_lo:[0,1] neg_hi:[0,1]
	v_pk_fma_f32 v[50:51], v[52:53], v[96:97], v[50:51]
	v_pk_fma_f32 v[170:171], v[52:53], v[104:105], v[170:171]
	v_pk_fma_f32 v[118:119], v[60:61], v[108:109], v[50:51] op_sel_hi:[1,0,1]
	v_pk_fma_f32 v[120:121], v[60:61], v[108:109], v[170:171] op_sel:[0,1,0]
	v_pk_mul_f32 v[50:51], v[48:49], v[110:111]
	v_pk_mul_f32 v[48:49], v[48:49], v[112:113]
	v_pk_fma_f32 v[50:51], v[46:47], v[106:107], v[50:51]
	v_pk_fma_f32 v[46:47], v[46:47], v[98:99], v[48:49]
	v_pk_fma_f32 v[48:49], v[44:45], v[118:119], v[50:51]
	v_pk_fma_f32 v[44:45], v[44:45], v[120:121], v[46:47]
	v_pk_fma_f32 v[48:49], v[42:43], v[114:115], v[48:49]
	v_pk_fma_f32 v[42:43], v[42:43], v[116:117], v[44:45]
	v_add_f32_e32 v4, v48, v49
	v_add_f32_e32 v42, v42, v43
	v_add_u32_e32 v168, 0x1e100, v253
	v_add_f32_dpp v4, v4, v4 quad_perm:[1,0,3,2] row_mask:0xf bank_mask:0xf bound_ctrl:1
	v_add_f32_dpp v42, v42, v42 quad_perm:[1,0,3,2] row_mask:0xf bank_mask:0xf bound_ctrl:1
	v_add_u32_e32 v169, 0x1e180, v253
	v_add_f32_dpp v4, v4, v4 quad_perm:[2,3,0,1] row_mask:0xf bank_mask:0xf bound_ctrl:1
	v_add_f32_dpp v42, v42, v42 quad_perm:[2,3,0,1] row_mask:0xf bank_mask:0xf bound_ctrl:1
	s_nop 0
	v_add_f32_dpp v4, v4, v4 row_half_mirror row_mask:0xf bank_mask:0xf bound_ctrl:1
	v_add_f32_dpp v42, v42, v42 row_half_mirror row_mask:0xf bank_mask:0xf bound_ctrl:1
	s_and_saveexec_b64 s[72:73], s[6:7]
	ds_write_b32 v168, v4
	ds_write_b32 v169, v42
; __device__ __forceinline__ void phase_rwkv(KP P, int l_, unsigned char* shm) {
;     ...
;                 f32x4 Aw0, Aw1, Akk0, Akk1, Ab0, Ab1, Ak0, Ak1, Ar0, Ar1; float Ava, Avb;
;                 f32x4 Bw0, Bw1, Bkk0, Bkk1, Bb0, Bb1, Bk0, Bk1, Br0, Br1; float Bva, Bvb;
;                 RW_LD(A, 0);
; #pragma unroll 2
;                 for (int tl = 0; tl < T; tl += 2) {
;                     RW_LD(B, tl + 1);
;                     RW_STEP(A, tl);
;                     RW_LD(A, tl + 2);
;                     RW_STEP(B, tl + 1);
;                 }
.LBB0_2521:
	s_or_b64 exec, exec, s[72:73]
	s_waitcnt lgkmcnt(8)
	v_pk_mul_f32 v[92:93], v[40:41], v[110:111]
	v_pk_mul_f32 v[40:41], v[40:41], v[112:113]
	v_pk_fma_f32 v[92:93], v[38:39], v[106:107], v[92:93]
	v_pk_fma_f32 v[38:39], v[38:39], v[98:99], v[40:41]
	s_waitcnt lgkmcnt(7)
	v_pk_fma_f32 v[40:41], v[36:37], v[118:119], v[92:93]
	v_pk_fma_f32 v[36:37], v[36:37], v[120:121], v[38:39]
	v_pk_fma_f32 v[40:41], v[34:35], v[114:115], v[40:41]
	v_pk_fma_f32 v[34:35], v[34:35], v[116:117], v[36:37]
	v_add_f32_e32 v4, v40, v41
	v_add_f32_e32 v34, v34, v35
	s_waitcnt lgkmcnt(0)
	v_add_f32_dpp v4, v4, v4 quad_perm:[1,0,3,2] row_mask:0xf bank_mask:0xf bound_ctrl:1
	v_add_f32_dpp v34, v34, v34 quad_perm:[1,0,3,2] row_mask:0xf bank_mask:0xf bound_ctrl:1
	ds_read_b128 v[62:65], v235 offset:512
	ds_read_b128 v[50:53], v235 offset:528
	ds_read_b128 v[78:81], v235 offset:8704
	ds_read_b128 v[74:77], v235 offset:8720
	ds_read_b128 v[66:69], v235 offset:16896
	ds_read_b128 v[54:57], v235 offset:16912
	ds_read_b128 v[70:73], v235 offset:25088
	ds_read_b128 v[58:61], v235 offset:25104
	ds_read_b128 v[46:49], v235 offset:33280
	ds_read_b128 v[42:45], v235 offset:33296
	ds_read2_b32 v[96:97], v186 offset0:128 offset1:160
	v_add_f32_dpp v4, v4, v4 quad_perm:[2,3,0,1] row_mask:0xf bank_mask:0xf bound_ctrl:1
	v_add_f32_dpp v34, v34, v34 quad_perm:[2,3,0,1] row_mask:0xf bank_mask:0xf bound_ctrl:1
	s_nop 0
	v_add_f32_dpp v4, v4, v4 row_half_mirror row_mask:0xf bank_mask:0xf bound_ctrl:1
	v_add_f32_dpp v34, v34, v34 row_half_mirror row_mask:0xf bank_mask:0xf bound_ctrl:1
	v_pk_mul_f32 v[38:39], v[26:27], v[4:5] op_sel_hi:[1,0] neg_lo:[0,1] neg_hi:[0,1]
	v_pk_mul_f32 v[26:27], v[26:27], v[34:35] op_sel_hi:[1,0] neg_lo:[0,1] neg_hi:[0,1]
	v_pk_fma_f32 v[38:39], v[22:23], v[106:107], v[38:39]
	v_pk_fma_f32 v[22:23], v[22:23], v[98:99], v[26:27]
	v_pk_fma_f32 v[92:93], v[30:31], v[90:91], v[38:39] op_sel_hi:[1,0,1]
	v_pk_fma_f32 v[94:95], v[30:31], v[90:91], v[22:23] op_sel:[0,1,0]
	v_pk_mul_f32 v[22:23], v[28:29], v[4:5] op_sel_hi:[1,0] neg_lo:[0,1] neg_hi:[0,1]
	v_pk_mul_f32 v[170:171], v[28:29], v[34:35] op_sel_hi:[1,0] neg_lo:[0,1] neg_hi:[0,1]
	v_pk_fma_f32 v[22:23], v[24:25], v[110:111], v[22:23]
	v_pk_fma_f32 v[170:171], v[24:25], v[112:113], v[170:171]
	v_pk_fma_f32 v[100:101], v[32:33], v[90:91], v[22:23] op_sel_hi:[1,0,1]
	v_pk_fma_f32 v[102:103], v[32:33], v[90:91], v[170:171] op_sel:[0,1,0]
	v_pk_mul_f32 v[22:23], v[14:15], v[4:5] op_sel_hi:[1,0] neg_lo:[0,1] neg_hi:[0,1]
	v_pk_mul_f32 v[14:15], v[14:15], v[34:35] op_sel_hi:[1,0] neg_lo:[0,1] neg_hi:[0,1]
	v_pk_fma_f32 v[22:23], v[10:11], v[114:115], v[22:23]
	v_pk_fma_f32 v[10:11], v[10:11], v[116:117], v[14:15]
	v_pk_fma_f32 v[104:105], v[18:19], v[90:91], v[22:23] op_sel_hi:[1,0,1]
	v_pk_fma_f32 v[108:109], v[18:19], v[90:91], v[10:11] op_sel:[0,1,0]
	v_pk_mul_f32 v[10:11], v[16:17], v[4:5] op_sel_hi:[1,0] neg_lo:[0,1] neg_hi:[0,1]
	v_pk_mul_f32 v[170:171], v[16:17], v[34:35] op_sel_hi:[1,0] neg_lo:[0,1] neg_hi:[0,1]
	v_pk_fma_f32 v[10:11], v[12:13], v[118:119], v[10:11]
	v_pk_fma_f32 v[170:171], v[12:13], v[120:121], v[170:171]
	v_pk_fma_f32 v[110:111], v[20:21], v[90:91], v[10:11] op_sel_hi:[1,0,1]
	v_pk_fma_f32 v[112:113], v[20:21], v[90:91], v[170:171] op_sel:[0,1,0]
	v_pk_mul_f32 v[10:11], v[8:9], v[100:101]
	v_pk_mul_f32 v[8:9], v[8:9], v[102:103]
	v_pk_fma_f32 v[10:11], v[6:7], v[92:93], v[10:11]
	v_pk_fma_f32 v[6:7], v[6:7], v[94:95], v[8:9]
	v_pk_fma_f32 v[8:9], v[2:3], v[110:111], v[10:11]
	v_pk_fma_f32 v[2:3], v[2:3], v[112:113], v[6:7]
	v_pk_fma_f32 v[8:9], v[0:1], v[104:105], v[8:9]
	v_pk_fma_f32 v[0:1], v[0:1], v[108:109], v[2:3]
	v_add_f32_e32 v2, v8, v9
	v_add_f32_e32 v0, v0, v1
	v_add_u32_e32 v168, 0x1e200, v253
	v_add_f32_dpp v1, v2, v2 quad_perm:[1,0,3,2] row_mask:0xf bank_mask:0xf bound_ctrl:1
	v_add_f32_dpp v2, v0, v0 quad_perm:[1,0,3,2] row_mask:0xf bank_mask:0xf bound_ctrl:1
	v_add_u32_e32 v169, 0x1e280, v253
	v_add_f32_dpp v0, v1, v1 quad_perm:[2,3,0,1] row_mask:0xf bank_mask:0xf bound_ctrl:1
	v_add_f32_dpp v1, v2, v2 quad_perm:[2,3,0,1] row_mask:0xf bank_mask:0xf bound_ctrl:1
	s_nop 0
	v_add_f32_dpp v0, v0, v0 row_half_mirror row_mask:0xf bank_mask:0xf bound_ctrl:1
	v_add_f32_dpp v1, v1, v1 row_half_mirror row_mask:0xf bank_mask:0xf bound_ctrl:1
	s_and_saveexec_b64 s[72:73], s[6:7]
	ds_write_b32 v168, v0
	ds_write_b32 v169, v1
; __device__ __forceinline__ void phase_rwkv(KP P, int l_, unsigned char* shm) {
;     ...
;                 f32x4 Aw0, Aw1, Akk0, Akk1, Ab0, Ab1, Ak0, Ak1, Ar0, Ar1; float Ava, Avb;
;                 f32x4 Bw0, Bw1, Bkk0, Bkk1, Bb0, Bb1, Bk0, Bk1, Br0, Br1; float Bva, Bvb;
;                 RW_LD(A, 0);
; #pragma unroll 2
;                 for (int tl = 0; tl < T; tl += 2) {
;                     RW_LD(B, tl + 1);
;                     RW_STEP(A, tl);
;                     RW_LD(A, tl + 2);
;                     RW_STEP(B, tl + 1);
;                 }
.LBB0_2523:
	s_or_b64 exec, exec, s[72:73]
	s_waitcnt lgkmcnt(8)
	v_pk_mul_f32 v[90:91], v[80:81], v[100:101]
	v_pk_mul_f32 v[80:81], v[80:81], v[102:103]
	v_pk_fma_f32 v[90:91], v[78:79], v[92:93], v[90:91]
	v_pk_fma_f32 v[78:79], v[78:79], v[94:95], v[80:81]
	s_waitcnt lgkmcnt(7)
	v_pk_fma_f32 v[80:81], v[76:77], v[110:111], v[90:91]
	v_pk_fma_f32 v[76:77], v[76:77], v[112:113], v[78:79]
	v_pk_fma_f32 v[80:81], v[74:75], v[104:105], v[80:81]
	v_pk_fma_f32 v[74:75], v[74:75], v[108:109], v[76:77]
	v_add_f32_e32 v76, v80, v81
	v_add_f32_e32 v74, v74, v75
	s_waitcnt lgkmcnt(0)
	v_mov_b32_e32 v78, v97
	v_add_f32_dpp v75, v76, v76 quad_perm:[1,0,3,2] row_mask:0xf bank_mask:0xf bound_ctrl:1
	v_add_f32_dpp v74, v74, v74 quad_perm:[1,0,3,2] row_mask:0xf bank_mask:0xf bound_ctrl:1
	ds_read_b128 v[10:13], v235 offset:768
	ds_read_b128 v[0:3], v235 offset:784
	ds_read_b128 v[38:41], v235 offset:8960
	ds_read_b128 v[34:37], v235 offset:8976
	ds_read_b128 v[26:29], v235 offset:17152
	ds_read_b128 v[6:9], v235 offset:17168
	ds_read2_b32 v[106:107], v186 offset0:192 offset1:224
	ds_read_b128 v[30:33], v235 offset:25344
	ds_read_b128 v[22:25], v235 offset:25360
	ds_read_b128 v[18:21], v235 offset:33536
	ds_read_b128 v[14:17], v235 offset:33552
	v_add_f32_dpp v75, v75, v75 quad_perm:[2,3,0,1] row_mask:0xf bank_mask:0xf bound_ctrl:1
	v_add_f32_dpp v76, v74, v74 quad_perm:[2,3,0,1] row_mask:0xf bank_mask:0xf bound_ctrl:1
	s_waitcnt lgkmcnt(4)
	v_add_f32_dpp v74, v75, v75 row_half_mirror row_mask:0xf bank_mask:0xf bound_ctrl:1
	v_add_f32_dpp v76, v76, v76 row_half_mirror row_mask:0xf bank_mask:0xf bound_ctrl:1
	v_pk_mul_f32 v[80:81], v[66:67], v[74:75] op_sel_hi:[1,0] neg_lo:[0,1] neg_hi:[0,1]
	v_pk_mul_f32 v[66:67], v[66:67], v[76:77] op_sel_hi:[1,0] neg_lo:[0,1] neg_hi:[0,1]
	v_pk_fma_f32 v[80:81], v[62:63], v[92:93], v[80:81]
	v_pk_fma_f32 v[62:63], v[62:63], v[94:95], v[66:67]
	v_pk_fma_f32 v[90:91], v[70:71], v[96:97], v[80:81] op_sel_hi:[1,0,1]
	v_pk_fma_f32 v[98:99], v[70:71], v[78:79], v[62:63] op_sel_hi:[1,0,1]
	v_pk_mul_f32 v[62:63], v[68:69], v[74:75] op_sel_hi:[1,0] neg_lo:[0,1] neg_hi:[0,1]
	v_pk_mul_f32 v[170:171], v[68:69], v[76:77] op_sel_hi:[1,0] neg_lo:[0,1] neg_hi:[0,1]
	v_pk_fma_f32 v[62:63], v[64:65], v[100:101], v[62:63]
	v_pk_fma_f32 v[170:171], v[64:65], v[102:103], v[170:171]
	v_pk_fma_f32 v[92:93], v[72:73], v[96:97], v[62:63] op_sel_hi:[1,0,1]
	v_pk_fma_f32 v[100:101], v[72:73], v[78:79], v[170:171] op_sel_hi:[1,0,1]
	v_pk_mul_f32 v[62:63], v[54:55], v[74:75] op_sel_hi:[1,0] neg_lo:[0,1] neg_hi:[0,1]
	v_pk_mul_f32 v[54:55], v[54:55], v[76:77] op_sel_hi:[1,0] neg_lo:[0,1] neg_hi:[0,1]
	v_pk_fma_f32 v[62:63], v[50:51], v[104:105], v[62:63]
	v_pk_fma_f32 v[50:51], v[50:51], v[108:109], v[54:55]
	v_pk_fma_f32 v[94:95], v[58:59], v[96:97], v[62:63] op_sel_hi:[1,0,1]
	v_pk_fma_f32 v[102:103], v[58:59], v[78:79], v[50:51] op_sel_hi:[1,0,1]
	v_pk_mul_f32 v[50:51], v[56:57], v[74:75] op_sel_hi:[1,0] neg_lo:[0,1] neg_hi:[0,1]
	v_pk_mul_f32 v[170:171], v[56:57], v[76:77] op_sel_hi:[1,0] neg_lo:[0,1] neg_hi:[0,1]
	v_pk_fma_f32 v[50:51], v[52:53], v[110:111], v[50:51]
	v_pk_fma_f32 v[170:171], v[52:53], v[112:113], v[170:171]
	v_pk_fma_f32 v[96:97], v[60:61], v[96:97], v[50:51] op_sel_hi:[1,0,1]
	v_pk_fma_f32 v[104:105], v[60:61], v[78:79], v[170:171] op_sel_hi:[1,0,1]
	v_pk_mul_f32 v[50:51], v[48:49], v[92:93]
	v_pk_mul_f32 v[48:49], v[48:49], v[100:101]
	v_pk_fma_f32 v[50:51], v[46:47], v[90:91], v[50:51]
	v_pk_fma_f32 v[46:47], v[46:47], v[98:99], v[48:49]
	v_pk_fma_f32 v[48:49], v[44:45], v[96:97], v[50:51]
	v_pk_fma_f32 v[44:45], v[44:45], v[104:105], v[46:47]
	v_pk_fma_f32 v[48:49], v[42:43], v[94:95], v[48:49]
	v_pk_fma_f32 v[42:43], v[42:43], v[102:103], v[44:45]
	v_add_f32_e32 v44, v48, v49
	v_add_f32_e32 v42, v42, v43
	v_add_u32_e32 v168, 0x1e300, v253
	v_add_f32_dpp v43, v44, v44 quad_perm:[1,0,3,2] row_mask:0xf bank_mask:0xf bound_ctrl:1
	v_add_f32_dpp v44, v42, v42 quad_perm:[1,0,3,2] row_mask:0xf bank_mask:0xf bound_ctrl:1
	v_add_u32_e32 v169, 0x1e380, v253
	v_add_f32_dpp v42, v43, v43 quad_perm:[2,3,0,1] row_mask:0xf bank_mask:0xf bound_ctrl:1
	v_add_f32_dpp v43, v44, v44 quad_perm:[2,3,0,1] row_mask:0xf bank_mask:0xf bound_ctrl:1
	s_nop 0
	v_add_f32_dpp v42, v42, v42 row_half_mirror row_mask:0xf bank_mask:0xf bound_ctrl:1
	v_add_f32_dpp v43, v43, v43 row_half_mirror row_mask:0xf bank_mask:0xf bound_ctrl:1
	s_and_saveexec_b64 s[72:73], s[6:7]
	ds_write_b32 v168, v42
	ds_write_b32 v169, v43
	s_branch .LBB0_2516
